# P8 K-loop: per-MFMA-block s_setprio flips removed; one static s_setprio 1 for the trailing wave half (waves 4-7) for the whole phase
# speedup vs baseline: 1.0046x; 1.0001x over previous
; #define PG8_STAGE(bufoff, gbase, voff) do { _Pragma("unroll") for (int _i = 0; _i < 2; ++_i) \
;         __builtin_amdgcn_global_load_lds((const unsigned*)((const char*)(gbase) + (voff)[_i]), (PG8_LAS unsigned*)(lds + (bufoff) + ldsw + _i * 8192), 16, 0, 0); } while (0)
; #define PG8_WAIT_V(n) asm volatile("s_waitcnt vmcnt(" #n ")" ::: "memory")
; #define PG8_BAR __builtin_amdgcn_s_barrier()
; template <class Epi, class Sched, bool ALIGN_EPI = false, bool SP2 = false>
; __device__ __forceinline__ void gemm_phase(PG8_LAS unsigned char* lds, const Gemm g, const Sched& S, const Epi& E) {
;     ...
;     const int tid = tid_l_, wid = __builtin_amdgcn_readfirstlane(tid >> 6), lane = tid & 63, wr = wid >> 2, wc = wid & 3, fr = lane & 15, fq = lane >> 4;
;     const int K = g.K, nt = K / BK;
;     unsigned voffA[2], voffB[2];
; #pragma unroll
;     for (int i = 0; i < 2; ++i) { int R, C; stage_rc(tid * 16 + i * 8192, R, C); const int Rb = Epi::PERM ? ((R & ~31) + perm32(R & 31)) : R;
;         voffA[i] = (unsigned)(R * K + C) * 2u; voffB[i] = (unsigned)(Rb * K + C) * 2u; }
;     ...
;     if constexpr (SP2) {
;         PG8_STAGE(PG8_SB(0, 0), cB, voffB); PG8_STAGE(PG8_SB(0, 1), cB + hstep, voffB); PG8_STAGE(PG8_SA(0, 0), cA, voffA); PG8_STAGE(PG8_SA(0, 1), cA + hstep, voffA);
;         if (wr == 1) PG8_BAR;
;         PG8_WAIT_V(2); PG8_BAR;
.LBB0_1166:
	s_or_b64 exec, exec, s[4:5]
	s_add_u32 s8, s78, 0xa000000
	s_addc_u32 s9, s79, 0
	v_mov_b32_e32 v11, v0
	s_waitcnt lgkmcnt(0)
	s_barrier
	s_cmpk_gt_i32 s2, 0x57f
	v_readfirstlane_b32 s0, v11
	s_cbranch_scc1 .LBB0_1182
	s_waitcnt vmcnt(0)
	v_readfirstlane_b32 s98, v0
	s_cmpk_lt_u32 s98, 0x100
	s_cbranch_scc1 .Lp8prio_lo
	s_setprio 1
.Lp8prio_lo:
	v_lshlrev_b32_e32 v1, 4, v11
	v_add_u32_e32 v2, 0x2000, v1
	v_ashrrev_i32_e32 v3, 31, v2
	v_lshrrev_b32_e32 v3, 22, v3
	v_add_u32_e32 v3, v2, v3
	v_ashrrev_i32_e32 v10, 10, v3
	v_mul_i32_i24_e32 v3, 0x400, v10
	v_sub_u32_e32 v2, v2, v3
	v_lshrrev_b32_e32 v3, 4, v2
	v_bitop3_b32 v2, v3, v2, 32 bitop3:0x6c
	v_ashrrev_i32_e32 v3, 31, v2
	v_lshrrev_b32_e32 v3, 26, v3
	v_add_u32_e32 v3, v2, v3
	v_lshlrev_b32_e32 v4, 3, v10
	v_ashrrev_i32_e32 v12, 6, v3
	v_and_b32_e32 v4, -16, v4
	v_add_u32_e32 v4, v12, v4
	v_and_b32_e32 v5, 3, v12
	s_mov_b32 s4, 0x1fffe0
	v_lshrrev_b32_e32 v6, 2, v4
	v_lshlrev_b32_e32 v7, 1, v4
	v_and_b32_e32 v3, 0xc0, v3
	v_and_or_b32 v5, v4, s4, v5
	v_and_b32_e32 v6, 4, v6
	v_and_b32_e32 v7, 24, v7
	v_sub_u32_e32 v2, v2, v3
	v_mov_b32_e32 v3, 1
	v_or3_b32 v5, v5, v6, v7
	v_lshlrev_b32_e32 v6, 5, v10
	v_ashrrev_i16_sdwa v2, v3, sext(v2) dst_sel:DWORD dst_unused:UNUSED_PAD src0_sel:DWORD src1_sel:BYTE_0
	v_and_b32_e32 v6, 32, v6
	v_bfe_i32 v13, v2, 0, 16
	v_add_lshl_u32 v2, v6, v13, 1
	v_lshl_add_u32 v130, v5, 11, v2
	v_lshl_add_u32 v132, v4, 11, v2
	v_bfe_i32 v2, v11, 27, 1
	v_lshrrev_b32_e32 v2, 22, v2
	v_add_u32_e32 v2, v1, v2
	v_and_b32_e32 v2, 0xfffffc00, v2
	v_sub_u32_e32 v1, v1, v2
	v_lshrrev_b32_e32 v2, 4, v1
	v_ashrrev_i32_e32 v4, 31, v11
	v_bitop3_b32 v1, v2, v1, 32 bitop3:0x6c
	v_lshrrev_b32_e32 v4, 26, v4
	v_ashrrev_i32_e32 v2, 31, v1
	v_add_u32_e32 v4, v11, v4
	v_lshrrev_b32_e32 v2, 26, v2
	v_ashrrev_i32_e32 v15, 6, v4
	v_add_u32_e32 v2, v1, v2
	v_lshlrev_b32_e32 v4, 3, v15
	v_ashrrev_i32_e32 v14, 6, v2
	v_and_b32_e32 v4, -16, v4
	v_add_u32_e32 v4, v14, v4
	v_and_b32_e32 v5, 3, v14
	s_ashr_i32 s13, s2, 31
	v_and_or_b32 v5, v4, s4, v5
	s_lshr_b32 s4, s13, 29
	s_add_i32 s4, s2, s4
	s_ashr_i32 s3, s0, 6
	s_ashr_i32 s5, s4, 3
	s_and_b32 s4, s4, -8
	s_ashr_i32 s1, s0, 8
	s_lshl_b32 s12, s3, 10
	s_sub_i32 s4, s2, s4
	s_cmp_lt_i32 s4, 0
	s_movk_i32 s34, 0xb1
	s_cselect_b32 s6, s34, 0xb0
	s_mul_i32 s4, s4, s6
	s_add_i32 s4, s4, s5
	s_mul_hi_i32 s5, s4, 0x2e8ba2e9
	s_lshr_b32 s6, s5, 31
	s_ashr_i32 s5, s5, 5
	s_add_i32 s5, s5, s6
	s_lshl_b32 s6, s5, 3
	s_mulk_i32 s5, 0xb0
	s_sub_i32 s5, s4, s5
	s_sext_i32_i16 s4, s5
	s_bfe_u32 s4, s4, 0x3001c
	s_add_i32 s7, s5, s4
	s_sext_i32_i16 s4, s7
	s_and_b32 s7, s7, 0xfff8
	s_sub_i32 s5, s5, s7
	s_sext_i32_i16 s5, s5
	v_lshrrev_b32_e32 v6, 2, v4
	v_lshlrev_b32_e32 v7, 1, v4
	v_and_b32_e32 v2, 0xc0, v2
	s_lshr_b32 s4, s4, 3
	s_add_i32 s38, s6, s5
	v_and_b32_e32 v6, 4, v6
	v_and_b32_e32 v7, 24, v7
	v_sub_u32_e32 v1, v1, v2
	s_ashr_i32 s39, s38, 31
	s_bfe_i64 s[10:11], s[4:5], 0x100000
	v_or3_b32 v5, v5, v6, v7
	v_lshlrev_b32_e32 v6, 5, v15
	v_ashrrev_i16_sdwa v1, v3, sext(v1) dst_sel:DWORD dst_unused:UNUSED_PAD src0_sel:DWORD src1_sel:BYTE_0
	s_lshl_b64 s[6:7], s[38:39], 19
	s_lshl_b64 s[10:11], s[10:11], 19
	v_and_b32_e32 v6, 32, v6
	v_bfe_i32 v16, v1, 0, 16
	s_add_u32 s42, s24, s10
	v_add_lshl_u32 v1, v6, v16, 1
	s_addc_u32 s43, s25, s11
	s_add_i32 s35, s12, 0
	v_lshl_add_u32 v134, v5, 11, v1
	s_add_i32 m0, s35, 0x10000
	v_lshl_add_u32 v136, v4, 11, v1
	global_load_lds_dwordx4 v134, s[42:43]
	s_add_i32 m0, s35, 0x12000
	s_add_u32 s10, s42, 0x40000
	global_load_lds_dwordx4 v130, s[42:43]
	s_addc_u32 s11, s43, 0
	s_add_i32 m0, s35, 0x14000
	v_mov_b32_e32 v135, 0
	global_load_lds_dwordx4 v134, s[10:11]
	s_add_i32 m0, s35, 0x16000
	s_add_u32 s40, s20, s6
	s_addc_u32 s41, s21, s7
	s_add_i32 s39, s35, 0x2000
	global_load_lds_dwordx4 v130, s[10:11]
	s_mov_b32 m0, s35
	s_add_u32 s6, s40, 0x40000
	global_load_lds_dwordx4 v136, s[40:41]
	s_mov_b32 m0, s39
	s_addc_u32 s7, s41, 0
	s_add_i32 s46, s35, 0x4000
	global_load_lds_dwordx4 v132, s[40:41]
	s_mov_b32 m0, s46
	s_add_i32 s47, s35, 0x6000
	global_load_lds_dwordx4 v136, s[6:7]
	s_mov_b32 m0, s47
	v_mov_b32_e32 v131, v135
	global_load_lds_dwordx4 v132, s[6:7]
	v_mov_b32_e32 v137, v135
	v_mov_b32_e32 v133, v135
	s_cmp_eq_u32 s1, 1
	s_mov_b32 s7, 0
	v_lshl_add_u64 v[8:9], s[42:43], 0, v[134:135]
	v_lshl_add_u64 v[6:7], s[42:43], 0, v[130:131]
	v_lshl_add_u64 v[2:3], s[40:41], 0, v[136:137]
	s_cselect_b64 s[10:11], -1, 0
	s_cmp_lg_u32 s1, 1
	v_lshl_add_u64 v[4:5], s[40:41], 0, v[132:133]
	s_cbranch_scc1 .LBB0_1169
	s_barrier

; #define PG8_STAGE(bufoff, gbase, voff) do { _Pragma("unroll") for (int _i = 0; _i < 2; ++_i) \
;         __builtin_amdgcn_global_load_lds((const unsigned*)((const char*)(gbase) + (voff)[_i]), (PG8_LAS unsigned*)(lds + (bufoff) + ldsw + _i * 8192), 16, 0, 0); } while (0)
; #define PG8_LDA(dst, b, h) do { _Pragma("unroll") for (int m = 0; m < 4; ++m) _Pragma("unroll") for (int k = 0; k < 2; ++k) dst[m][k] = *(const PG8_LAS bf16x8*)(lds + PG8_SA(b, h) + aoff + m * 2048 + k * 1024); } while (0)
; #define PG8_LDB(dst, b, h) do { _Pragma("unroll") for (int n = 0; n < 2; ++n) _Pragma("unroll") for (int k = 0; k < 2; ++k) dst[n][k] = *(const PG8_LAS bf16x8*)(lds + PG8_SB(b, h) + boff + n * 2048 + k * 1024); } while (0)
; #define PG8_MMA(ai, bj, At, Bt) do { __builtin_amdgcn_s_setprio(1); _Pragma("unroll") for (int m = 0; m < 4; ++m) _Pragma("unroll") for (int n = 0; n < 2; ++n) _Pragma("unroll") for (int k = 0; k < 2; ++k) \
;         acc[ai][bj][m][n] = __builtin_amdgcn_mfma_f32_16x16x32_bf16(Bt[n][k], At[m][k], acc[ai][bj][m][n], 0, 0, 0); __builtin_amdgcn_s_setprio(0); } while (0)
; #define PG8_WAIT_V(n) asm volatile("s_waitcnt vmcnt(" #n ")" ::: "memory")
; #define PG8_WAIT_L(n) asm volatile("s_waitcnt lgkmcnt(" #n ")" ::: "memory")
; #define PG8_BAR __builtin_amdgcn_s_barrier()
; #define PG8_SCHED __builtin_amdgcn_sched_barrier(0)
; template <class Epi, class Sched, bool ALIGN_EPI = false, bool SP2 = false>
; __device__ __forceinline__ void gemm_phase(PG8_LAS unsigned char* lds, const Gemm g, const Sched& S, const Epi& E) {
;     ...
;             PG8_LDB(B0, 0, 0); PG8_LDB(B1, 0, 1); PG8_SCHED; PG8_LDA(At, 0, 0); PG8_STAGE(PG8_SA(1, 1), a1 + hstep, voffA);
;             PG8_WAIT_V(8); PG8_WAIT_L(0); PG8_BAR; PG8_MMA(0, 0, At, B0); PG8_MMA(0, 1, At, B1); PG8_BAR; PG8_SCHED;
;             PG8_LDA(At, 0, 1); PG8_STAGE(PG8_SB(0, 0), b2, voffB); PG8_STAGE(PG8_SB(0, 1), b2 + hstep, voffB); PG8_STAGE(PG8_SA(0, 0), a2, voffA);
;             PG8_WAIT_V(8); PG8_WAIT_L(0); PG8_BAR; PG8_MMA(1, 0, At, B0); PG8_MMA(1, 1, At, B1); PG8_BAR; PG8_SCHED;
.LBB0_1175:
	ds_read_b128 v[152:155], v148
	ds_read_b128 v[156:159], v148 offset:1024
	ds_read_b128 v[160:163], v148 offset:2048
	ds_read_b128 v[164:167], v148 offset:3072
	ds_read_b128 v[168:171], v149
	ds_read_b128 v[172:175], v149 offset:1024
	ds_read_b128 v[176:179], v149 offset:2048
	ds_read_b128 v[180:183], v149 offset:3072
	s_add_u32 s3, s40, 0xfffc0080
	s_addc_u32 s42, s41, -1
	s_cmp_eq_u32 s55, 12
	s_cselect_b32 s45, s0, s42
	s_cselect_b32 s44, s1, s3
	s_cselect_b32 s43, s27, s54
	s_cselect_b32 s42, s29, s53
	v_lshl_add_u64 v[216:217], s[40:41], 0, v[138:139]
	s_add_i32 m0, s35, 0xc000
	ds_read_b128 v[184:187], v150
	ds_read_b128 v[188:191], v150 offset:1024
	ds_read_b128 v[192:195], v150 offset:2048
	ds_read_b128 v[196:199], v150 offset:3072
	ds_read_b128 v[200:203], v150 offset:4096
	ds_read_b128 v[204:207], v150 offset:5120
	ds_read_b128 v[208:211], v150 offset:6144
	ds_read_b128 v[212:215], v150 offset:7168
	global_load_lds_dwordx4 v[216:217], off
	v_lshl_add_u64 v[216:217], s[40:41], 0, v[140:141]
	s_add_i32 m0, s35, 0xe000
	s_nop 0
	global_load_lds_dwordx4 v[216:217], off
	s_waitcnt vmcnt(8)
	s_waitcnt lgkmcnt(0)
	s_barrier
	s_waitcnt lgkmcnt(0)
	v_mfma_f32_16x16x32_bf16 v[126:129], v[152:155], v[184:187], v[126:129]
	v_mfma_f32_16x16x32_bf16 v[122:125], v[160:163], v[184:187], v[122:125]
	v_mfma_f32_16x16x32_bf16 v[110:113], v[152:155], v[192:195], v[110:113]
	v_mfma_f32_16x16x32_bf16 v[106:109], v[160:163], v[192:195], v[106:109]
	v_mfma_f32_16x16x32_bf16 v[94:97], v[152:155], v[200:203], v[94:97]
	v_mfma_f32_16x16x32_bf16 v[90:93], v[160:163], v[200:203], v[90:93]
	v_mfma_f32_16x16x32_bf16 v[78:81], v[152:155], v[208:211], v[78:81]
	v_mfma_f32_16x16x32_bf16 v[74:77], v[160:163], v[208:211], v[74:77]
	v_mfma_f32_16x16x32_bf16 v[126:129], v[156:159], v[188:191], v[126:129]
	v_mfma_f32_16x16x32_bf16 v[122:125], v[164:167], v[188:191], v[122:125]
	v_mfma_f32_16x16x32_bf16 v[110:113], v[156:159], v[196:199], v[110:113]
	v_mfma_f32_16x16x32_bf16 v[106:109], v[164:167], v[196:199], v[106:109]
	v_mfma_f32_16x16x32_bf16 v[94:97], v[156:159], v[204:207], v[94:97]
	v_mfma_f32_16x16x32_bf16 v[90:93], v[164:167], v[204:207], v[90:93]
	v_mfma_f32_16x16x32_bf16 v[78:81], v[156:159], v[212:215], v[78:81]
	v_mfma_f32_16x16x32_bf16 v[74:77], v[164:167], v[212:215], v[74:77]
	v_mfma_f32_16x16x32_bf16 v[118:121], v[168:171], v[184:187], v[118:121]
	v_mfma_f32_16x16x32_bf16 v[114:117], v[176:179], v[184:187], v[114:117]
	v_mfma_f32_16x16x32_bf16 v[102:105], v[168:171], v[192:195], v[102:105]
	v_mfma_f32_16x16x32_bf16 v[98:101], v[176:179], v[192:195], v[98:101]
	v_mfma_f32_16x16x32_bf16 v[86:89], v[168:171], v[200:203], v[86:89]
	v_mfma_f32_16x16x32_bf16 v[82:85], v[176:179], v[200:203], v[82:85]
	v_mfma_f32_16x16x32_bf16 v[70:73], v[168:171], v[208:211], v[70:73]
	v_mfma_f32_16x16x32_bf16 v[66:69], v[176:179], v[208:211], v[66:69]
	v_mfma_f32_16x16x32_bf16 v[118:121], v[172:175], v[188:191], v[118:121]
	v_mfma_f32_16x16x32_bf16 v[114:117], v[180:183], v[188:191], v[114:117]
	v_mfma_f32_16x16x32_bf16 v[102:105], v[172:175], v[196:199], v[102:105]
	v_mfma_f32_16x16x32_bf16 v[98:101], v[180:183], v[196:199], v[98:101]
	v_mfma_f32_16x16x32_bf16 v[86:89], v[172:175], v[204:207], v[86:89]
	v_mfma_f32_16x16x32_bf16 v[82:85], v[180:183], v[204:207], v[82:85]
	v_mfma_f32_16x16x32_bf16 v[70:73], v[172:175], v[212:215], v[70:73]
	v_mfma_f32_16x16x32_bf16 v[66:69], v[180:183], v[212:215], v[66:69]
	s_barrier
	s_add_i32 s3, s33, s12
	v_lshl_add_u64 v[216:217], s[42:43], 0, v[134:135]
	s_mov_b32 m0, s3
	ds_read_b128 v[184:187], v150 offset:16384
	ds_read_b128 v[188:191], v150 offset:17408
	ds_read_b128 v[192:195], v150 offset:18432
	ds_read_b128 v[196:199], v150 offset:19456
	ds_read_b128 v[200:203], v150 offset:20480
	ds_read_b128 v[204:207], v150 offset:21504
	ds_read_b128 v[208:211], v150 offset:22528
	ds_read_b128 v[212:215], v150 offset:23552
	global_load_lds_dwordx4 v[216:217], off
	s_add_i32 m0, s3, 0x2000
	s_add_u32 s56, s42, 0x40000
	v_lshl_add_u64 v[218:219], s[42:43], 0, v[130:131]
	s_addc_u32 s57, s43, 0
	s_add_i32 s3, s50, s12
	global_load_lds_dwordx4 v[218:219], off
	v_lshl_add_u64 v[220:221], s[56:57], 0, v[134:135]
	s_mov_b32 m0, s3
	v_lshl_add_u64 v[222:223], s[44:45], 0, v[132:133]
	global_load_lds_dwordx4 v[220:221], off
	v_lshl_add_u64 v[220:221], s[56:57], 0, v[130:131]
	s_add_i32 m0, s3, 0x2000
	s_nop 0
	global_load_lds_dwordx4 v[220:221], off
	v_lshl_add_u64 v[220:221], s[44:45], 0, v[136:137]
	s_mov_b32 m0, s35
	s_nop 0
	global_load_lds_dwordx4 v[220:221], off
	s_mov_b32 m0, s39
	s_nop 0
	global_load_lds_dwordx4 v[222:223], off
	s_waitcnt vmcnt(8)
	s_waitcnt lgkmcnt(0)
	s_barrier
; #define PG8_STAGE(bufoff, gbase, voff) do { _Pragma("unroll") for (int _i = 0; _i < 2; ++_i) \
;         __builtin_amdgcn_global_load_lds((const unsigned*)((const char*)(gbase) + (voff)[_i]), (PG8_LAS unsigned*)(lds + (bufoff) + ldsw + _i * 8192), 16, 0, 0); } while (0)
; #define PG8_LDA(dst, b, h) do { _Pragma("unroll") for (int m = 0; m < 4; ++m) _Pragma("unroll") for (int k = 0; k < 2; ++k) dst[m][k] = *(const PG8_LAS bf16x8*)(lds + PG8_SA(b, h) + aoff + m * 2048 + k * 1024); } while (0)
; #define PG8_LDB(dst, b, h) do { _Pragma("unroll") for (int n = 0; n < 2; ++n) _Pragma("unroll") for (int k = 0; k < 2; ++k) dst[n][k] = *(const PG8_LAS bf16x8*)(lds + PG8_SB(b, h) + boff + n * 2048 + k * 1024); } while (0)
; #define PG8_MMA(ai, bj, At, Bt) do { __builtin_amdgcn_s_setprio(1); _Pragma("unroll") for (int m = 0; m < 4; ++m) _Pragma("unroll") for (int n = 0; n < 2; ++n) _Pragma("unroll") for (int k = 0; k < 2; ++k) \
;         acc[ai][bj][m][n] = __builtin_amdgcn_mfma_f32_16x16x32_bf16(Bt[n][k], At[m][k], acc[ai][bj][m][n], 0, 0, 0); __builtin_amdgcn_s_setprio(0); } while (0)
; #define PG8_WAIT_V(n) asm volatile("s_waitcnt vmcnt(" #n ")" ::: "memory")
; #define PG8_WAIT_L(n) asm volatile("s_waitcnt lgkmcnt(" #n ")" ::: "memory")
; #define PG8_BAR __builtin_amdgcn_s_barrier()
; #define PG8_SCHED __builtin_amdgcn_sched_barrier(0)
; template <class Epi, class Sched, bool ALIGN_EPI = false, bool SP2 = false>
; __device__ __forceinline__ void gemm_phase(PG8_LAS unsigned char* lds, const Gemm g, const Sched& S, const Epi& E) {
;     ...
;             PG8_WAIT_V(8); PG8_WAIT_L(0); PG8_BAR; PG8_MMA(1, 0, At, B0); PG8_MMA(1, 1, At, B1); PG8_BAR; PG8_SCHED;
;             PG8_LDB(B0, 1, 0); PG8_LDB(B1, 1, 1); PG8_SCHED; PG8_LDA(At, 1, 0); PG8_STAGE(PG8_SA(0, 1), a2 + hstep, voffA);
;             PG8_WAIT_V(8); PG8_WAIT_L(0); PG8_BAR; PG8_MMA(0, 0, At, B0); PG8_MMA(0, 1, At, B1); PG8_BAR; PG8_SCHED;
	s_waitcnt lgkmcnt(0)
	v_mfma_f32_16x16x32_bf16 v[62:65], v[152:155], v[184:187], v[62:65]
	v_mfma_f32_16x16x32_bf16 v[58:61], v[160:163], v[184:187], v[58:61]
	v_mfma_f32_16x16x32_bf16 v[46:49], v[152:155], v[192:195], v[46:49]
	v_mfma_f32_16x16x32_bf16 v[42:45], v[160:163], v[192:195], v[42:45]
	v_mfma_f32_16x16x32_bf16 v[30:33], v[152:155], v[200:203], v[30:33]
	v_mfma_f32_16x16x32_bf16 v[26:29], v[160:163], v[200:203], v[26:29]
	v_mfma_f32_16x16x32_bf16 v[14:17], v[152:155], v[208:211], v[14:17]
	v_mfma_f32_16x16x32_bf16 v[10:13], v[160:163], v[208:211], v[10:13]
	v_mfma_f32_16x16x32_bf16 v[62:65], v[156:159], v[188:191], v[62:65]
	v_mfma_f32_16x16x32_bf16 v[58:61], v[164:167], v[188:191], v[58:61]
	v_mfma_f32_16x16x32_bf16 v[46:49], v[156:159], v[196:199], v[46:49]
	v_mfma_f32_16x16x32_bf16 v[42:45], v[164:167], v[196:199], v[42:45]
	v_mfma_f32_16x16x32_bf16 v[30:33], v[156:159], v[204:207], v[30:33]
	v_mfma_f32_16x16x32_bf16 v[26:29], v[164:167], v[204:207], v[26:29]
	v_mfma_f32_16x16x32_bf16 v[14:17], v[156:159], v[212:215], v[14:17]
	v_mfma_f32_16x16x32_bf16 v[10:13], v[164:167], v[212:215], v[10:13]
	v_mfma_f32_16x16x32_bf16 v[54:57], v[168:171], v[184:187], v[54:57]
	v_mfma_f32_16x16x32_bf16 v[50:53], v[176:179], v[184:187], v[50:53]
	v_mfma_f32_16x16x32_bf16 v[38:41], v[168:171], v[192:195], v[38:41]
	v_mfma_f32_16x16x32_bf16 v[34:37], v[176:179], v[192:195], v[34:37]
	v_mfma_f32_16x16x32_bf16 v[22:25], v[168:171], v[200:203], v[22:25]
	v_mfma_f32_16x16x32_bf16 v[18:21], v[176:179], v[200:203], v[18:21]
	v_mfma_f32_16x16x32_bf16 v[6:9], v[168:171], v[208:211], v[6:9]
	v_mfma_f32_16x16x32_bf16 v[2:5], v[176:179], v[208:211], v[2:5]
	v_mfma_f32_16x16x32_bf16 v[54:57], v[172:175], v[188:191], v[54:57]
	v_mfma_f32_16x16x32_bf16 v[50:53], v[180:183], v[188:191], v[50:53]
	v_mfma_f32_16x16x32_bf16 v[38:41], v[172:175], v[196:199], v[38:41]
	v_mfma_f32_16x16x32_bf16 v[34:37], v[180:183], v[196:199], v[34:37]
	v_mfma_f32_16x16x32_bf16 v[22:25], v[172:175], v[204:207], v[22:25]
	v_mfma_f32_16x16x32_bf16 v[18:21], v[180:183], v[204:207], v[18:21]
	v_mfma_f32_16x16x32_bf16 v[6:9], v[172:175], v[212:215], v[6:9]
	v_mfma_f32_16x16x32_bf16 v[2:5], v[180:183], v[212:215], v[2:5]
	s_barrier
	s_add_i32 s3, 0, 0x18000
	v_add_u32_e32 v151, s3, v146
	s_add_i32 s56, 0, 0x1c000
	ds_read_b128 v[152:155], v151
	ds_read_b128 v[156:159], v151 offset:1024
	ds_read_b128 v[160:163], v151 offset:2048
	ds_read_b128 v[164:167], v151 offset:3072
	v_add_u32_e32 v151, s56, v146
	ds_read_b128 v[168:171], v151
	ds_read_b128 v[172:175], v151 offset:1024
	ds_read_b128 v[176:179], v151 offset:2048
	ds_read_b128 v[180:183], v151 offset:3072
	s_add_u32 s44, s44, 0x40000
	s_addc_u32 s45, s45, 0
	s_mov_b32 m0, s46
	v_lshl_add_u64 v[224:225], s[44:45], 0, v[136:137]
	ds_read_b128 v[184:187], v150 offset:32768
	ds_read_b128 v[188:191], v150 offset:33792
	ds_read_b128 v[192:195], v150 offset:34816
	ds_read_b128 v[196:199], v150 offset:35840
	ds_read_b128 v[200:203], v150 offset:36864
	ds_read_b128 v[204:207], v150 offset:37888
	ds_read_b128 v[208:211], v150 offset:38912
	ds_read_b128 v[212:215], v150 offset:39936
	global_load_lds_dwordx4 v[224:225], off
	v_lshl_add_u64 v[224:225], s[44:45], 0, v[132:133]
	s_mov_b32 m0, s47
	s_nop 0
	global_load_lds_dwordx4 v[224:225], off
	s_waitcnt vmcnt(8)
	s_waitcnt lgkmcnt(0)
	s_barrier
	s_waitcnt lgkmcnt(0)
	v_mfma_f32_16x16x32_bf16 v[126:129], v[152:155], v[184:187], v[126:129]
	v_mfma_f32_16x16x32_bf16 v[122:125], v[160:163], v[184:187], v[122:125]
	v_mfma_f32_16x16x32_bf16 v[110:113], v[152:155], v[192:195], v[110:113]
	v_mfma_f32_16x16x32_bf16 v[106:109], v[160:163], v[192:195], v[106:109]
	v_mfma_f32_16x16x32_bf16 v[94:97], v[152:155], v[200:203], v[94:97]
	v_mfma_f32_16x16x32_bf16 v[90:93], v[160:163], v[200:203], v[90:93]
	v_mfma_f32_16x16x32_bf16 v[78:81], v[152:155], v[208:211], v[78:81]
	v_mfma_f32_16x16x32_bf16 v[74:77], v[160:163], v[208:211], v[74:77]
	v_mfma_f32_16x16x32_bf16 v[126:129], v[156:159], v[188:191], v[126:129]
	v_mfma_f32_16x16x32_bf16 v[122:125], v[164:167], v[188:191], v[122:125]
	v_mfma_f32_16x16x32_bf16 v[110:113], v[156:159], v[196:199], v[110:113]
	v_mfma_f32_16x16x32_bf16 v[106:109], v[164:167], v[196:199], v[106:109]
	v_mfma_f32_16x16x32_bf16 v[94:97], v[156:159], v[204:207], v[94:97]
	v_mfma_f32_16x16x32_bf16 v[90:93], v[164:167], v[204:207], v[90:93]
	v_mfma_f32_16x16x32_bf16 v[78:81], v[156:159], v[212:215], v[78:81]
	v_mfma_f32_16x16x32_bf16 v[74:77], v[164:167], v[212:215], v[74:77]
	v_mfma_f32_16x16x32_bf16 v[118:121], v[168:171], v[184:187], v[118:121]
	v_mfma_f32_16x16x32_bf16 v[114:117], v[176:179], v[184:187], v[114:117]
	v_mfma_f32_16x16x32_bf16 v[102:105], v[168:171], v[192:195], v[102:105]
	v_mfma_f32_16x16x32_bf16 v[98:101], v[176:179], v[192:195], v[98:101]
	v_mfma_f32_16x16x32_bf16 v[86:89], v[168:171], v[200:203], v[86:89]
	v_mfma_f32_16x16x32_bf16 v[82:85], v[176:179], v[200:203], v[82:85]
	v_mfma_f32_16x16x32_bf16 v[70:73], v[168:171], v[208:211], v[70:73]
	v_mfma_f32_16x16x32_bf16 v[66:69], v[176:179], v[208:211], v[66:69]
	v_mfma_f32_16x16x32_bf16 v[118:121], v[172:175], v[188:191], v[118:121]
	v_mfma_f32_16x16x32_bf16 v[114:117], v[180:183], v[188:191], v[114:117]
	v_mfma_f32_16x16x32_bf16 v[102:105], v[172:175], v[196:199], v[102:105]
	v_mfma_f32_16x16x32_bf16 v[98:101], v[180:183], v[196:199], v[98:101]
	v_mfma_f32_16x16x32_bf16 v[86:89], v[172:175], v[204:207], v[86:89]
	v_mfma_f32_16x16x32_bf16 v[82:85], v[180:183], v[204:207], v[82:85]
	v_mfma_f32_16x16x32_bf16 v[70:73], v[172:175], v[212:215], v[70:73]
	v_mfma_f32_16x16x32_bf16 v[66:69], v[180:183], v[212:215], v[66:69]
	s_barrier
; #define PG8_STAGE(bufoff, gbase, voff) do { _Pragma("unroll") for (int _i = 0; _i < 2; ++_i) \
;         __builtin_amdgcn_global_load_lds((const unsigned*)((const char*)(gbase) + (voff)[_i]), (PG8_LAS unsigned*)(lds + (bufoff) + ldsw + _i * 8192), 16, 0, 0); } while (0)
; #define PG8_LDA(dst, b, h) do { _Pragma("unroll") for (int m = 0; m < 4; ++m) _Pragma("unroll") for (int k = 0; k < 2; ++k) dst[m][k] = *(const PG8_LAS bf16x8*)(lds + PG8_SA(b, h) + aoff + m * 2048 + k * 1024); } while (0)
; #define PG8_MMA(ai, bj, At, Bt) do { __builtin_amdgcn_s_setprio(1); _Pragma("unroll") for (int m = 0; m < 4; ++m) _Pragma("unroll") for (int n = 0; n < 2; ++n) _Pragma("unroll") for (int k = 0; k < 2; ++k) \
;         acc[ai][bj][m][n] = __builtin_amdgcn_mfma_f32_16x16x32_bf16(Bt[n][k], At[m][k], acc[ai][bj][m][n], 0, 0, 0); __builtin_amdgcn_s_setprio(0); } while (0)
; #define PG8_WAIT_V(n) asm volatile("s_waitcnt vmcnt(" #n ")" ::: "memory")
; #define PG8_WAIT_L(n) asm volatile("s_waitcnt lgkmcnt(" #n ")" ::: "memory")
; #define PG8_BAR __builtin_amdgcn_s_barrier()
; #define PG8_SCHED __builtin_amdgcn_sched_barrier(0)
; template <class Epi, class Sched, bool ALIGN_EPI = false, bool SP2 = false>
; __device__ __forceinline__ void gemm_phase(PG8_LAS unsigned char* lds, const Gemm g, const Sched& S, const Epi& E) {
;     ...
;             PG8_WAIT_V(8); PG8_WAIT_L(0); PG8_BAR; PG8_MMA(0, 0, At, B0); PG8_MMA(0, 1, At, B1); PG8_BAR; PG8_SCHED;
;             PG8_LDA(At, 1, 1); PG8_STAGE(PG8_SB(1, 0), b3, voffB); PG8_STAGE(PG8_SB(1, 1), b3 + hstep, voffB); PG8_STAGE(PG8_SA(1, 0), a3, voffA);
;             PG8_WAIT_V(8); PG8_WAIT_L(0); PG8_BAR; PG8_MMA(1, 0, At, B0); PG8_MMA(1, 1, At, B1); PG8_BAR; PG8_SCHED;
	s_add_i32 s3, s3, s12
	v_lshl_add_u64 v[216:217], v[216:217], 0, s[14:15]
	s_mov_b32 m0, s3
	ds_read_b128 v[184:187], v150 offset:49152
	ds_read_b128 v[188:191], v150 offset:50176
	ds_read_b128 v[192:195], v150 offset:51200
	ds_read_b128 v[196:199], v150 offset:52224
	ds_read_b128 v[200:203], v150 offset:53248
	ds_read_b128 v[204:207], v150 offset:54272
	ds_read_b128 v[208:211], v150 offset:55296
	ds_read_b128 v[212:215], v150 offset:56320
	global_load_lds_dwordx4 v[216:217], off
	s_add_i32 m0, s3, 0x2000
	s_add_u32 s42, s42, 0x40080
	v_lshl_add_u64 v[216:217], v[218:219], 0, s[14:15]
	s_addc_u32 s43, s43, 0
	s_add_i32 s3, s56, s12
	global_load_lds_dwordx4 v[216:217], off
	v_lshl_add_u64 v[216:217], s[42:43], 0, v[134:135]
	s_mov_b32 m0, s3
	s_nop 0
	global_load_lds_dwordx4 v[216:217], off
	v_lshl_add_u64 v[216:217], s[42:43], 0, v[130:131]
	s_add_i32 m0, s3, 0x2000
	s_nop 0
	global_load_lds_dwordx4 v[216:217], off
	v_lshl_add_u64 v[216:217], v[220:221], 0, s[14:15]
	s_mov_b32 m0, s48
	s_nop 0
	global_load_lds_dwordx4 v[216:217], off
	v_lshl_add_u64 v[216:217], v[222:223], 0, s[14:15]
	s_mov_b32 m0, s49
	s_nop 0
	global_load_lds_dwordx4 v[216:217], off
	s_waitcnt vmcnt(8)
	s_waitcnt lgkmcnt(0)
	s_barrier
	s_waitcnt lgkmcnt(0)
	v_mfma_f32_16x16x32_bf16 v[62:65], v[152:155], v[184:187], v[62:65]
	v_mfma_f32_16x16x32_bf16 v[58:61], v[160:163], v[184:187], v[58:61]
	v_mfma_f32_16x16x32_bf16 v[46:49], v[152:155], v[192:195], v[46:49]
	v_mfma_f32_16x16x32_bf16 v[42:45], v[160:163], v[192:195], v[42:45]
	v_mfma_f32_16x16x32_bf16 v[30:33], v[152:155], v[200:203], v[30:33]
	v_mfma_f32_16x16x32_bf16 v[26:29], v[160:163], v[200:203], v[26:29]
	v_mfma_f32_16x16x32_bf16 v[14:17], v[152:155], v[208:211], v[14:17]
	v_mfma_f32_16x16x32_bf16 v[10:13], v[160:163], v[208:211], v[10:13]
	v_mfma_f32_16x16x32_bf16 v[62:65], v[156:159], v[188:191], v[62:65]
	v_mfma_f32_16x16x32_bf16 v[58:61], v[164:167], v[188:191], v[58:61]
	v_mfma_f32_16x16x32_bf16 v[46:49], v[156:159], v[196:199], v[46:49]
	v_mfma_f32_16x16x32_bf16 v[42:45], v[164:167], v[196:199], v[42:45]
	v_mfma_f32_16x16x32_bf16 v[30:33], v[156:159], v[204:207], v[30:33]
	v_mfma_f32_16x16x32_bf16 v[26:29], v[164:167], v[204:207], v[26:29]
	v_mfma_f32_16x16x32_bf16 v[14:17], v[156:159], v[212:215], v[14:17]
	v_mfma_f32_16x16x32_bf16 v[10:13], v[164:167], v[212:215], v[10:13]
	v_mfma_f32_16x16x32_bf16 v[54:57], v[168:171], v[184:187], v[54:57]
	v_mfma_f32_16x16x32_bf16 v[50:53], v[176:179], v[184:187], v[50:53]
	v_mfma_f32_16x16x32_bf16 v[38:41], v[168:171], v[192:195], v[38:41]
	v_mfma_f32_16x16x32_bf16 v[34:37], v[176:179], v[192:195], v[34:37]
	v_mfma_f32_16x16x32_bf16 v[22:25], v[168:171], v[200:203], v[22:25]
	v_mfma_f32_16x16x32_bf16 v[18:21], v[176:179], v[200:203], v[18:21]
	v_mfma_f32_16x16x32_bf16 v[6:9], v[168:171], v[208:211], v[6:9]
	v_mfma_f32_16x16x32_bf16 v[2:5], v[176:179], v[208:211], v[2:5]
	v_mfma_f32_16x16x32_bf16 v[54:57], v[172:175], v[188:191], v[54:57]
	v_mfma_f32_16x16x32_bf16 v[50:53], v[180:183], v[188:191], v[50:53]
	v_mfma_f32_16x16x32_bf16 v[38:41], v[172:175], v[196:199], v[38:41]
	v_mfma_f32_16x16x32_bf16 v[34:37], v[180:183], v[196:199], v[34:37]
	v_mfma_f32_16x16x32_bf16 v[22:25], v[172:175], v[204:207], v[22:25]
	v_mfma_f32_16x16x32_bf16 v[18:21], v[180:183], v[204:207], v[18:21]
	v_mfma_f32_16x16x32_bf16 v[6:9], v[172:175], v[212:215], v[6:9]
	v_mfma_f32_16x16x32_bf16 v[2:5], v[180:183], v[212:215], v[2:5]
	s_barrier
	s_add_i32 s55, s55, 2
	s_add_u32 s40, s40, 0x100
	s_addc_u32 s41, s41, 0
	s_add_u32 s53, s53, 0x100
	s_addc_u32 s54, s54, 0
	s_cmp_gt_u32 s55, 13
	s_cbranch_scc0 .LBB0_1175
	s_and_b64 vcc, exec, s[16:17]
	s_cbranch_vccz .LBB0_1178
	s_barrier

; #define PG8_WAIT_V(n) asm volatile("s_waitcnt vmcnt(" #n ")" ::: "memory")
; #define PG8_BAR __builtin_amdgcn_s_barrier()
; template <class Epi, class Sched, bool ALIGN_EPI = false, bool SP2 = false>
; __device__ __forceinline__ void gemm_phase(PG8_LAS unsigned char* lds, const Gemm g, const Sched& S, const Epi& E) {
;     ...
;     PG8_WAIT_V(0);
;     if constexpr (!ALIGN_EPI) { if (wr == 0) PG8_BAR; }
;     PG8_BAR;
.LBB0_1181:
	s_setprio 0
	s_waitcnt vmcnt(0)
	s_barrier
